# GEMM phases: accumulator clear with 64 v_mov_b64 instead of 128 v_mov_b32 per tile (on top of v5)
# baseline (speedup 1.0000x reference)
; template <class Epi, class Sched, bool ALIGN_EPI = false, bool SP2 = false, bool F16 = false, bool TOKPERM = false>
; __device__ __forceinline__ void gemm_phase(PG8_LAS unsigned char* lds, const Gemm g, const Sched& S, const Epi& E, int wv) {
;     ...
;         const bool has_next = S.next(ui + 1, nxt);
;         const char* nA = has_next ? (const char*)g.A + (size_t)nxt.pm * tstep : cA; const char* nB = has_next ? (const char*)g.Bt + (size_t)nxt.pn * tstep : cB;
;     ...
; #pragma unroll
;         for (int a = 0; a < 2; ++a)
; #pragma unroll
;             for (int b = 0; b < 2; ++b)
; #pragma unroll
;                 for (int m = 0; m < 4; ++m)
; #pragma unroll
;                     for (int n = 0; n < 2; ++n) acc[a][b][m][n] = (f32x4){0.f, 0.f, 0.f, 0.f};
.LBB0_180:
	s_ashr_i32 s51, s50, 31
	s_lshl_b64 s[52:53], s[50:51], 19
	s_add_u32 s52, s40, s52
	s_addc_u32 s53, s41, s53
	s_and_b64 s[54:55], s[2:3], exec
	s_cselect_b32 s51, s53, s7
	s_cselect_b32 s77, s52, s6
	s_ashr_i32 s49, s48, 31
	s_lshl_b64 s[54:55], s[48:49], 19
	s_add_u32 s54, s33, s54
	s_addc_u32 s55, s36, s55
	s_and_b64 s[56:57], s[2:3], exec
	s_cselect_b32 s49, s55, s9
	s_cselect_b32 s78, s54, s8
	s_add_u32 s6, s6, 0x40080
	s_addc_u32 s7, s7, 0
	s_add_u32 s79, s8, 0x100
	v_mov_b64_e32 v[0:1], 0
	s_addc_u32 s80, s9, 0
	s_mov_b32 s81, -2
	v_mov_b64_e32 v[2:3], 0
	v_mov_b64_e32 v[4:5], 0
	v_mov_b64_e32 v[6:7], 0
	v_mov_b64_e32 v[16:17], 0
	v_mov_b64_e32 v[18:19], 0
	v_mov_b64_e32 v[20:21], 0
	v_mov_b64_e32 v[22:23], 0
	v_mov_b64_e32 v[32:33], 0
	v_mov_b64_e32 v[34:35], 0
	v_mov_b64_e32 v[36:37], 0
	v_mov_b64_e32 v[38:39], 0
	v_mov_b64_e32 v[48:49], 0
	v_mov_b64_e32 v[50:51], 0
	v_mov_b64_e32 v[52:53], 0
	v_mov_b64_e32 v[54:55], 0
	v_mov_b64_e32 v[8:9], 0
	v_mov_b64_e32 v[10:11], 0
	v_mov_b64_e32 v[12:13], 0
	v_mov_b64_e32 v[14:15], 0
	v_mov_b64_e32 v[24:25], 0
	v_mov_b64_e32 v[26:27], 0
	v_mov_b64_e32 v[28:29], 0
	v_mov_b64_e32 v[30:31], 0
	v_mov_b64_e32 v[40:41], 0
	v_mov_b64_e32 v[42:43], 0
	v_mov_b64_e32 v[44:45], 0
	v_mov_b64_e32 v[46:47], 0
	v_mov_b64_e32 v[56:57], 0
	v_mov_b64_e32 v[58:59], 0
	v_mov_b64_e32 v[60:61], 0
	v_mov_b64_e32 v[62:63], 0
	v_mov_b64_e32 v[64:65], 0
	v_mov_b64_e32 v[66:67], 0
	v_mov_b64_e32 v[68:69], 0
	v_mov_b64_e32 v[70:71], 0
	v_mov_b64_e32 v[80:81], 0
	v_mov_b64_e32 v[82:83], 0
	v_mov_b64_e32 v[84:85], 0
	v_mov_b64_e32 v[86:87], 0
	v_mov_b64_e32 v[96:97], 0
	v_mov_b64_e32 v[98:99], 0
	v_mov_b64_e32 v[100:101], 0
	v_mov_b64_e32 v[102:103], 0
	v_mov_b64_e32 v[112:113], 0
	v_mov_b64_e32 v[114:115], 0
	v_mov_b64_e32 v[120:121], 0
	v_mov_b64_e32 v[122:123], 0
	v_mov_b64_e32 v[72:73], 0
	v_mov_b64_e32 v[74:75], 0
	v_mov_b64_e32 v[76:77], 0
	v_mov_b64_e32 v[78:79], 0
	v_mov_b64_e32 v[88:89], 0
	v_mov_b64_e32 v[90:91], 0
	v_mov_b64_e32 v[92:93], 0
	v_mov_b64_e32 v[94:95], 0
	v_mov_b64_e32 v[104:105], 0
	v_mov_b64_e32 v[106:107], 0
	v_mov_b64_e32 v[108:109], 0
	v_mov_b64_e32 v[110:111], 0
	v_mov_b64_e32 v[116:117], 0
	v_mov_b64_e32 v[118:119], 0
	v_mov_b64_e32 v[124:125], 0
	v_mov_b64_e32 v[126:127], 0

; template <class Epi, class Sched, bool ALIGN_EPI = false, bool SP2 = false, bool F16 = false, bool TOKPERM = false>
; __device__ __forceinline__ void gemm_phase(PG8_LAS unsigned char* lds, const Gemm g, const Sched& S, const Epi& E, int wv) {
;     ...
; #pragma unroll
;         for (int a = 0; a < 2; ++a)
; #pragma unroll
;             for (int b = 0; b < 2; ++b)
; #pragma unroll
;                 for (int m = 0; m < 4; ++m)
; #pragma unroll
;                     for (int n = 0; n < 2; ++n) acc[a][b][m][n] = (f32x4){0.f, 0.f, 0.f, 0.f};
.LBB0_296:
	s_add_u32 s68, s18, 0x100
	v_mov_b64_e32 v[0:1], 0
	s_addc_u32 s69, s19, 0
	s_mov_b32 s70, -2
	s_waitcnt lgkmcnt(0)
	v_mov_b64_e32 v[2:3], 0
	v_mov_b64_e32 v[4:5], 0
	v_mov_b64_e32 v[6:7], 0
	v_mov_b64_e32 v[16:17], 0
	v_mov_b64_e32 v[18:19], 0
	v_mov_b64_e32 v[20:21], 0
	v_mov_b64_e32 v[22:23], 0
	v_mov_b64_e32 v[32:33], 0
	v_mov_b64_e32 v[34:35], 0
	v_mov_b64_e32 v[36:37], 0
	v_mov_b64_e32 v[38:39], 0
	v_mov_b64_e32 v[48:49], 0
	v_mov_b64_e32 v[50:51], 0
	v_mov_b64_e32 v[52:53], 0
	v_mov_b64_e32 v[54:55], 0
	v_mov_b64_e32 v[8:9], 0
	v_mov_b64_e32 v[10:11], 0
	v_mov_b64_e32 v[12:13], 0
	v_mov_b64_e32 v[14:15], 0
	v_mov_b64_e32 v[24:25], 0
	v_mov_b64_e32 v[26:27], 0
	v_mov_b64_e32 v[28:29], 0
	v_mov_b64_e32 v[30:31], 0
	v_mov_b64_e32 v[40:41], 0
	v_mov_b64_e32 v[42:43], 0
	v_mov_b64_e32 v[44:45], 0
	v_mov_b64_e32 v[46:47], 0
	v_mov_b64_e32 v[56:57], 0
	v_mov_b64_e32 v[58:59], 0
	v_mov_b64_e32 v[60:61], 0
	v_mov_b64_e32 v[62:63], 0
	v_mov_b64_e32 v[64:65], 0
	v_mov_b64_e32 v[66:67], 0
	v_mov_b64_e32 v[68:69], 0
	v_mov_b64_e32 v[70:71], 0
	v_mov_b64_e32 v[80:81], 0
	v_mov_b64_e32 v[82:83], 0
	v_mov_b64_e32 v[84:85], 0
	v_mov_b64_e32 v[86:87], 0
	v_mov_b64_e32 v[96:97], 0
	v_mov_b64_e32 v[98:99], 0
	v_mov_b64_e32 v[100:101], 0
	v_mov_b64_e32 v[102:103], 0
	v_mov_b64_e32 v[112:113], 0
	v_mov_b64_e32 v[114:115], 0
	v_mov_b64_e32 v[116:117], 0
	v_mov_b64_e32 v[118:119], 0
	v_mov_b64_e32 v[72:73], 0
	v_mov_b64_e32 v[74:75], 0
	v_mov_b64_e32 v[76:77], 0
	v_mov_b64_e32 v[78:79], 0
	v_mov_b64_e32 v[88:89], 0
	v_mov_b64_e32 v[90:91], 0
	v_mov_b64_e32 v[92:93], 0
	v_mov_b64_e32 v[94:95], 0
	v_mov_b64_e32 v[104:105], 0
	v_mov_b64_e32 v[106:107], 0
	v_mov_b64_e32 v[108:109], 0
	v_mov_b64_e32 v[110:111], 0
	v_mov_b64_e32 v[120:121], 0
	v_mov_b64_e32 v[122:123], 0
	v_mov_b64_e32 v[124:125], 0
	v_mov_b64_e32 v[126:127], 0

; template <class Epi, class Sched, bool ALIGN_EPI = false, bool SP2 = false, bool F16 = false, bool TOKPERM = false>
; __device__ __forceinline__ void gemm_phase(PG8_LAS unsigned char* lds, const Gemm g, const Sched& S, const Epi& E, int wv) {
;     ...
;         const bool has_next = S.next(ui + 1, nxt);
;         const char* nA = has_next ? (const char*)g.A + (size_t)nxt.pm * tstep : cA; const char* nB = has_next ? (const char*)g.Bt + (size_t)nxt.pn * tstep : cB;
;     ...
; #pragma unroll
;         for (int a = 0; a < 2; ++a)
; #pragma unroll
;             for (int b = 0; b < 2; ++b)
; #pragma unroll
;                 for (int m = 0; m < 4; ++m)
; #pragma unroll
;                     for (int n = 0; n < 2; ++n) acc[a][b][m][n] = (f32x4){0.f, 0.f, 0.f, 0.f};
.LBB0_381:
	s_ashr_i32 s71, s70, 31
	s_lshl_b64 s[10:11], s[70:71], 19
	s_add_u32 s72, s40, s10
	s_addc_u32 s73, s41, s11
	s_and_b64 s[10:11], s[4:5], exec
	s_cselect_b32 s12, s73, s7
	s_cselect_b32 s13, s72, s6
	s_ashr_i32 s69, s68, 31
	s_lshl_b64 s[10:11], s[68:69], 19
	s_add_u32 s74, s46, s10
	s_addc_u32 s75, s47, s11
	s_and_b64 s[10:11], s[4:5], exec
	s_cselect_b32 s59, s75, s9
	s_cselect_b32 s64, s74, s8
	s_add_u32 s6, s6, 0x40080
	s_addc_u32 s7, s7, 0
	s_add_u32 s69, s8, 0x100
	v_mov_b64_e32 v[0:1], 0
	s_addc_u32 s71, s9, 0
	s_mov_b32 s76, -2
	s_waitcnt lgkmcnt(0)
	v_mov_b64_e32 v[2:3], 0
	v_mov_b64_e32 v[4:5], 0
	v_mov_b64_e32 v[6:7], 0
	v_mov_b64_e32 v[16:17], 0
	v_mov_b64_e32 v[18:19], 0
	v_mov_b64_e32 v[20:21], 0
	v_mov_b64_e32 v[22:23], 0
	v_mov_b64_e32 v[32:33], 0
	v_mov_b64_e32 v[34:35], 0
	v_mov_b64_e32 v[36:37], 0
	v_mov_b64_e32 v[38:39], 0
	v_mov_b64_e32 v[48:49], 0
	v_mov_b64_e32 v[50:51], 0
	v_mov_b64_e32 v[52:53], 0
	v_mov_b64_e32 v[54:55], 0
	v_mov_b64_e32 v[8:9], 0
	v_mov_b64_e32 v[10:11], 0
	v_mov_b64_e32 v[12:13], 0
	v_mov_b64_e32 v[14:15], 0
	v_mov_b64_e32 v[24:25], 0
	v_mov_b64_e32 v[26:27], 0
	v_mov_b64_e32 v[28:29], 0
	v_mov_b64_e32 v[30:31], 0
	v_mov_b64_e32 v[40:41], 0
	v_mov_b64_e32 v[42:43], 0
	v_mov_b64_e32 v[44:45], 0
	v_mov_b64_e32 v[46:47], 0
	v_mov_b64_e32 v[56:57], 0
	v_mov_b64_e32 v[58:59], 0
	v_mov_b64_e32 v[60:61], 0
	v_mov_b64_e32 v[62:63], 0
	v_mov_b64_e32 v[64:65], 0
	v_mov_b64_e32 v[66:67], 0
	v_mov_b64_e32 v[68:69], 0
	v_mov_b64_e32 v[70:71], 0
	v_mov_b64_e32 v[80:81], 0
	v_mov_b64_e32 v[82:83], 0
	v_mov_b64_e32 v[84:85], 0
	v_mov_b64_e32 v[86:87], 0
	v_mov_b64_e32 v[96:97], 0
	v_mov_b64_e32 v[98:99], 0
	v_mov_b64_e32 v[100:101], 0
	v_mov_b64_e32 v[102:103], 0
	v_mov_b64_e32 v[112:113], 0
	v_mov_b64_e32 v[114:115], 0
	v_mov_b64_e32 v[116:117], 0
	v_mov_b64_e32 v[118:119], 0
	v_mov_b64_e32 v[72:73], 0
	v_mov_b64_e32 v[74:75], 0
	v_mov_b64_e32 v[76:77], 0
	v_mov_b64_e32 v[78:79], 0
	v_mov_b64_e32 v[88:89], 0
	v_mov_b64_e32 v[90:91], 0
	v_mov_b64_e32 v[92:93], 0
	v_mov_b64_e32 v[94:95], 0
	v_mov_b64_e32 v[104:105], 0
	v_mov_b64_e32 v[106:107], 0
	v_mov_b64_e32 v[108:109], 0
	v_mov_b64_e32 v[110:111], 0
	v_mov_b64_e32 v[120:121], 0
	v_mov_b64_e32 v[122:123], 0
	v_mov_b64_e32 v[124:125], 0
	v_mov_b64_e32 v[126:127], 0

; template <class Epi, class Sched, bool ALIGN_EPI = false, bool SP2 = false, bool F16 = false, bool TOKPERM = false>
; __device__ __forceinline__ void gemm_phase(PG8_LAS unsigned char* lds, const Gemm g, const Sched& S, const Epi& E, int wv) {
;     ...
;         const bool has_next = S.next(ui + 1, nxt);
;         const char* nA = has_next ? (const char*)g.A + (size_t)nxt.pm * tstep : cA; const char* nB = has_next ? (const char*)g.Bt + (size_t)nxt.pn * tstep : cB;
;     ...
; #pragma unroll
;         for (int a = 0; a < 2; ++a)
; #pragma unroll
;             for (int b = 0; b < 2; ++b)
; #pragma unroll
;                 for (int m = 0; m < 4; ++m)
; #pragma unroll
;                     for (int n = 0; n < 2; ++n) acc[a][b][m][n] = (f32x4){0.f, 0.f, 0.f, 0.f};
.LBB0_684:
	s_ashr_i32 s13, s12, 31
	v_cmp_lt_i64_e32 vcc, s[16:17], v[142:143]
	s_lshl_b64 s[16:17], s[12:13], 19
	s_add_u32 s16, s30, s16
	s_addc_u32 s17, s31, s17
	s_and_b64 s[18:19], vcc, exec
	s_cselect_b32 s13, s17, s53
	s_cselect_b32 s49, s16, s52
	s_ashr_i32 s11, s10, 31
	s_lshl_b64 s[18:19], s[10:11], 19
	s_add_u32 s18, s14, s18
	s_addc_u32 s19, s15, s19
	s_and_b64 s[56:57], vcc, exec
	s_cselect_b32 s11, s19, s55
	s_cselect_b32 s66, s18, s54
	s_add_u32 s52, s52, 0x40080
	s_addc_u32 s53, s53, 0
	s_add_u32 s67, s54, 0x100
	v_mov_b64_e32 v[0:1], 0
	s_addc_u32 s68, s55, 0
	s_mov_b32 s69, -2
	s_waitcnt lgkmcnt(0)
	v_mov_b64_e32 v[2:3], 0
	v_mov_b64_e32 v[4:5], 0
	v_mov_b64_e32 v[6:7], 0
	v_mov_b64_e32 v[16:17], 0
	v_mov_b64_e32 v[18:19], 0
	v_mov_b64_e32 v[20:21], 0
	v_mov_b64_e32 v[22:23], 0
	v_mov_b64_e32 v[32:33], 0
	v_mov_b64_e32 v[34:35], 0
	v_mov_b64_e32 v[36:37], 0
	v_mov_b64_e32 v[38:39], 0
	v_mov_b64_e32 v[48:49], 0
	v_mov_b64_e32 v[50:51], 0
	v_mov_b64_e32 v[52:53], 0
	v_mov_b64_e32 v[54:55], 0
	v_mov_b64_e32 v[8:9], 0
	v_mov_b64_e32 v[10:11], 0
	v_mov_b64_e32 v[12:13], 0
	v_mov_b64_e32 v[14:15], 0
	v_mov_b64_e32 v[24:25], 0
	v_mov_b64_e32 v[26:27], 0
	v_mov_b64_e32 v[28:29], 0
	v_mov_b64_e32 v[30:31], 0
	v_mov_b64_e32 v[40:41], 0
	v_mov_b64_e32 v[42:43], 0
	v_mov_b64_e32 v[44:45], 0
	v_mov_b64_e32 v[46:47], 0
	v_mov_b64_e32 v[56:57], 0
	v_mov_b64_e32 v[58:59], 0
	v_mov_b64_e32 v[60:61], 0
	v_mov_b64_e32 v[62:63], 0
	v_mov_b64_e32 v[64:65], 0
	v_mov_b64_e32 v[66:67], 0
	v_mov_b64_e32 v[68:69], 0
	v_mov_b64_e32 v[70:71], 0
	v_mov_b64_e32 v[80:81], 0
	v_mov_b64_e32 v[82:83], 0
	v_mov_b64_e32 v[84:85], 0
	v_mov_b64_e32 v[86:87], 0
	v_mov_b64_e32 v[96:97], 0
	v_mov_b64_e32 v[98:99], 0
	v_mov_b64_e32 v[100:101], 0
	v_mov_b64_e32 v[102:103], 0
	v_mov_b64_e32 v[112:113], 0
	v_mov_b64_e32 v[114:115], 0
	v_mov_b64_e32 v[116:117], 0
	v_mov_b64_e32 v[118:119], 0
	v_mov_b64_e32 v[72:73], 0
	v_mov_b64_e32 v[74:75], 0
	v_mov_b64_e32 v[76:77], 0
	v_mov_b64_e32 v[78:79], 0
	v_mov_b64_e32 v[88:89], 0
	v_mov_b64_e32 v[90:91], 0
	v_mov_b64_e32 v[92:93], 0
	v_mov_b64_e32 v[94:95], 0
	v_mov_b64_e32 v[104:105], 0
	v_mov_b64_e32 v[106:107], 0
	v_mov_b64_e32 v[108:109], 0
	v_mov_b64_e32 v[110:111], 0
	v_mov_b64_e32 v[120:121], 0
	v_mov_b64_e32 v[122:123], 0
	v_mov_b64_e32 v[124:125], 0
	v_mov_b64_e32 v[126:127], 0

; template <class Epi, class Sched, bool ALIGN_EPI = false, bool SP2 = false, bool F16 = false, bool TOKPERM = false>
; __device__ __forceinline__ void gemm_phase(PG8_LAS unsigned char* lds, const Gemm g, const Sched& S, const Epi& E, int wv) {
;     ...
;         const bool has_next = S.next(ui + 1, nxt);
;         const char* nA = has_next ? (const char*)g.A + (size_t)nxt.pm * tstep : cA; const char* nB = has_next ? (const char*)g.Bt + (size_t)nxt.pn * tstep : cB;
;     ...
; #pragma unroll
;         for (int a = 0; a < 2; ++a)
; #pragma unroll
;             for (int b = 0; b < 2; ++b)
; #pragma unroll
;                 for (int m = 0; m < 4; ++m)
; #pragma unroll
;                     for (int n = 0; n < 2; ++n) acc[a][b][m][n] = (f32x4){0.f, 0.f, 0.f, 0.f};
.LBB0_767:
	s_ashr_i32 s53, s52, 31
	s_lshl_b64 s[54:55], s[52:53], 19
	s_add_u32 s54, s40, s54
	s_addc_u32 s55, s41, s55
	s_and_b64 s[56:57], s[6:7], exec
	s_cselect_b32 s53, s55, s11
	s_cselect_b32 s70, s54, s10
	s_ashr_i32 s51, s50, 31
	s_lshl_b64 s[56:57], s[50:51], 19
	s_add_u32 s56, s0, s56
	s_addc_u32 s57, s1, s57
	s_and_b64 s[58:59], s[6:7], exec
	s_cselect_b32 s51, s57, s13
	s_cselect_b32 s71, s56, s12
	s_add_u32 s10, s10, 0x40080
	s_addc_u32 s11, s11, 0
	s_add_u32 s72, s12, 0x100
	v_mov_b64_e32 v[0:1], 0
	s_addc_u32 s73, s13, 0
	s_mov_b32 s74, -2
	v_mov_b64_e32 v[2:3], 0
	v_mov_b64_e32 v[4:5], 0
	v_mov_b64_e32 v[6:7], 0
	v_mov_b64_e32 v[16:17], 0
	v_mov_b64_e32 v[18:19], 0
	v_mov_b64_e32 v[20:21], 0
	v_mov_b64_e32 v[22:23], 0
	v_mov_b64_e32 v[32:33], 0
	v_mov_b64_e32 v[34:35], 0
	v_mov_b64_e32 v[36:37], 0
	v_mov_b64_e32 v[38:39], 0
	v_mov_b64_e32 v[48:49], 0
	v_mov_b64_e32 v[50:51], 0
	v_mov_b64_e32 v[52:53], 0
	v_mov_b64_e32 v[54:55], 0
	v_mov_b64_e32 v[8:9], 0
	v_mov_b64_e32 v[10:11], 0
	v_mov_b64_e32 v[12:13], 0
	v_mov_b64_e32 v[14:15], 0
	v_mov_b64_e32 v[24:25], 0
	v_mov_b64_e32 v[26:27], 0
	v_mov_b64_e32 v[28:29], 0
	v_mov_b64_e32 v[30:31], 0
	v_mov_b64_e32 v[40:41], 0
	v_mov_b64_e32 v[42:43], 0
	v_mov_b64_e32 v[44:45], 0
	v_mov_b64_e32 v[46:47], 0
	v_mov_b64_e32 v[56:57], 0
	v_mov_b64_e32 v[58:59], 0
	v_mov_b64_e32 v[60:61], 0
	v_mov_b64_e32 v[62:63], 0
	v_mov_b64_e32 v[64:65], 0
	v_mov_b64_e32 v[66:67], 0
	v_mov_b64_e32 v[68:69], 0
	v_mov_b64_e32 v[70:71], 0
	v_mov_b64_e32 v[80:81], 0
	v_mov_b64_e32 v[82:83], 0
	v_mov_b64_e32 v[84:85], 0
	v_mov_b64_e32 v[86:87], 0
	v_mov_b64_e32 v[96:97], 0
	v_mov_b64_e32 v[98:99], 0
	v_mov_b64_e32 v[100:101], 0
	v_mov_b64_e32 v[102:103], 0
	v_mov_b64_e32 v[112:113], 0
	v_mov_b64_e32 v[114:115], 0
	v_mov_b64_e32 v[120:121], 0
	v_mov_b64_e32 v[122:123], 0
	v_mov_b64_e32 v[72:73], 0
	v_mov_b64_e32 v[74:75], 0
	v_mov_b64_e32 v[76:77], 0
	v_mov_b64_e32 v[78:79], 0
	v_mov_b64_e32 v[88:89], 0
	v_mov_b64_e32 v[90:91], 0
	v_mov_b64_e32 v[92:93], 0
	v_mov_b64_e32 v[94:95], 0
	v_mov_b64_e32 v[104:105], 0
	v_mov_b64_e32 v[106:107], 0
	v_mov_b64_e32 v[108:109], 0
	v_mov_b64_e32 v[110:111], 0
	v_mov_b64_e32 v[116:117], 0
	v_mov_b64_e32 v[118:119], 0
	v_mov_b64_e32 v[124:125], 0
	v_mov_b64_e32 v[126:127], 0

; template <class Epi, class Sched, bool ALIGN_EPI = false, bool SP2 = false, bool F16 = false, bool TOKPERM = false>
; __device__ __forceinline__ void gemm_phase(PG8_LAS unsigned char* lds, const Gemm g, const Sched& S, const Epi& E, int wv) {
;     ...
; #pragma unroll
;         for (int a = 0; a < 2; ++a)
; #pragma unroll
;             for (int b = 0; b < 2; ++b)
; #pragma unroll
;                 for (int m = 0; m < 4; ++m)
; #pragma unroll
;                     for (int n = 0; n < 2; ++n) acc[a][b][m][n] = (f32x4){0.f, 0.f, 0.f, 0.f};
.LBB0_866:
	s_add_u32 s65, s18, 0x100
	v_mov_b64_e32 v[0:1], 0
	s_addc_u32 s66, s19, 0
	s_mov_b32 s67, -2
	s_waitcnt lgkmcnt(0)
	v_mov_b64_e32 v[2:3], 0
	v_mov_b64_e32 v[4:5], 0
	v_mov_b64_e32 v[6:7], 0
	v_mov_b64_e32 v[16:17], 0
	v_mov_b64_e32 v[18:19], 0
	v_mov_b64_e32 v[20:21], 0
	v_mov_b64_e32 v[22:23], 0
	v_mov_b64_e32 v[32:33], 0
	v_mov_b64_e32 v[34:35], 0
	v_mov_b64_e32 v[36:37], 0
	v_mov_b64_e32 v[38:39], 0
	v_mov_b64_e32 v[48:49], 0
	v_mov_b64_e32 v[50:51], 0
	v_mov_b64_e32 v[52:53], 0
	v_mov_b64_e32 v[54:55], 0
	v_mov_b64_e32 v[8:9], 0
	v_mov_b64_e32 v[10:11], 0
	v_mov_b64_e32 v[12:13], 0
	v_mov_b64_e32 v[14:15], 0
	v_mov_b64_e32 v[24:25], 0
	v_mov_b64_e32 v[26:27], 0
	v_mov_b64_e32 v[28:29], 0
	v_mov_b64_e32 v[30:31], 0
	v_mov_b64_e32 v[40:41], 0
	v_mov_b64_e32 v[42:43], 0
	v_mov_b64_e32 v[44:45], 0
	v_mov_b64_e32 v[46:47], 0
	v_mov_b64_e32 v[56:57], 0
	v_mov_b64_e32 v[58:59], 0
	v_mov_b64_e32 v[60:61], 0
	v_mov_b64_e32 v[62:63], 0
	v_mov_b64_e32 v[64:65], 0
	v_mov_b64_e32 v[66:67], 0
	v_mov_b64_e32 v[68:69], 0
	v_mov_b64_e32 v[70:71], 0
	v_mov_b64_e32 v[80:81], 0
	v_mov_b64_e32 v[82:83], 0
	v_mov_b64_e32 v[84:85], 0
	v_mov_b64_e32 v[86:87], 0
	v_mov_b64_e32 v[96:97], 0
	v_mov_b64_e32 v[98:99], 0
	v_mov_b64_e32 v[100:101], 0
	v_mov_b64_e32 v[102:103], 0
	v_mov_b64_e32 v[112:113], 0
	v_mov_b64_e32 v[114:115], 0
	v_mov_b64_e32 v[116:117], 0
	v_mov_b64_e32 v[118:119], 0
	v_mov_b64_e32 v[72:73], 0
	v_mov_b64_e32 v[74:75], 0
	v_mov_b64_e32 v[76:77], 0
	v_mov_b64_e32 v[78:79], 0
	v_mov_b64_e32 v[88:89], 0
	v_mov_b64_e32 v[90:91], 0
	v_mov_b64_e32 v[92:93], 0
	v_mov_b64_e32 v[94:95], 0
	v_mov_b64_e32 v[104:105], 0
	v_mov_b64_e32 v[106:107], 0
	v_mov_b64_e32 v[108:109], 0
	v_mov_b64_e32 v[110:111], 0
	v_mov_b64_e32 v[120:121], 0
	v_mov_b64_e32 v[122:123], 0
	v_mov_b64_e32 v[124:125], 0
	v_mov_b64_e32 v[126:127], 0

; template <class Epi, class Sched, bool ALIGN_EPI = false, bool SP2 = false, bool F16 = false, bool TOKPERM = false>
; __device__ __forceinline__ void gemm_phase(PG8_LAS unsigned char* lds, const Gemm g, const Sched& S, const Epi& E, int wv) {
;     ...
;         const bool has_next = S.next(ui + 1, nxt);
;         const char* nA = has_next ? (const char*)g.A + (size_t)nxt.pm * tstep : cA; const char* nB = has_next ? (const char*)g.Bt + (size_t)nxt.pn * tstep : cB;
;     ...
; #pragma unroll
;         for (int a = 0; a < 2; ++a)
; #pragma unroll
;             for (int b = 0; b < 2; ++b)
; #pragma unroll
;                 for (int m = 0; m < 4; ++m)
; #pragma unroll
;                     for (int n = 0; n < 2; ++n) acc[a][b][m][n] = (f32x4){0.f, 0.f, 0.f, 0.f};
.LBB0_949:
	s_ashr_i32 s51, s50, 31
	s_lshl_b64 s[52:53], s[50:51], 19
	s_add_u32 s52, s40, s52
	s_addc_u32 s53, s41, s53
	s_and_b64 s[54:55], s[6:7], exec
	s_cselect_b32 s51, s53, s11
	s_cselect_b32 s70, s52, s10
	s_ashr_i32 s49, s48, 31
	s_lshl_b64 s[54:55], s[48:49], 19
	s_add_u32 s54, s0, s54
	s_addc_u32 s55, s1, s55
	s_and_b64 s[56:57], s[6:7], exec
	s_cselect_b32 s49, s55, s13
	s_cselect_b32 s71, s54, s12
	s_add_u32 s10, s10, 0x40080
	s_addc_u32 s11, s11, 0
	s_add_u32 s72, s12, 0x100
	v_mov_b64_e32 v[0:1], 0
	s_addc_u32 s73, s13, 0
	s_mov_b32 s74, -2
	v_mov_b64_e32 v[2:3], 0
	v_mov_b64_e32 v[4:5], 0
	v_mov_b64_e32 v[6:7], 0
	v_mov_b64_e32 v[16:17], 0
	v_mov_b64_e32 v[18:19], 0
	v_mov_b64_e32 v[20:21], 0
	v_mov_b64_e32 v[22:23], 0
	v_mov_b64_e32 v[32:33], 0
	v_mov_b64_e32 v[34:35], 0
	v_mov_b64_e32 v[36:37], 0
	v_mov_b64_e32 v[38:39], 0
	v_mov_b64_e32 v[48:49], 0
	v_mov_b64_e32 v[50:51], 0
	v_mov_b64_e32 v[52:53], 0
	v_mov_b64_e32 v[54:55], 0
	v_mov_b64_e32 v[8:9], 0
	v_mov_b64_e32 v[10:11], 0
	v_mov_b64_e32 v[12:13], 0
	v_mov_b64_e32 v[14:15], 0
	v_mov_b64_e32 v[24:25], 0
	v_mov_b64_e32 v[26:27], 0
	v_mov_b64_e32 v[28:29], 0
	v_mov_b64_e32 v[30:31], 0
	v_mov_b64_e32 v[40:41], 0
	v_mov_b64_e32 v[42:43], 0
	v_mov_b64_e32 v[44:45], 0
	v_mov_b64_e32 v[46:47], 0
	v_mov_b64_e32 v[56:57], 0
	v_mov_b64_e32 v[58:59], 0
	v_mov_b64_e32 v[60:61], 0
	v_mov_b64_e32 v[62:63], 0
	v_mov_b64_e32 v[64:65], 0
	v_mov_b64_e32 v[66:67], 0
	v_mov_b64_e32 v[68:69], 0
	v_mov_b64_e32 v[70:71], 0
	v_mov_b64_e32 v[80:81], 0
	v_mov_b64_e32 v[82:83], 0
	v_mov_b64_e32 v[84:85], 0
	v_mov_b64_e32 v[86:87], 0
	v_mov_b64_e32 v[96:97], 0
	v_mov_b64_e32 v[98:99], 0
	v_mov_b64_e32 v[100:101], 0
	v_mov_b64_e32 v[102:103], 0
	v_mov_b64_e32 v[112:113], 0
	v_mov_b64_e32 v[114:115], 0
	v_mov_b64_e32 v[120:121], 0
	v_mov_b64_e32 v[122:123], 0
	v_mov_b64_e32 v[72:73], 0
	v_mov_b64_e32 v[74:75], 0
	v_mov_b64_e32 v[76:77], 0
	v_mov_b64_e32 v[78:79], 0
	v_mov_b64_e32 v[88:89], 0
	v_mov_b64_e32 v[90:91], 0
	v_mov_b64_e32 v[92:93], 0
	v_mov_b64_e32 v[94:95], 0
	v_mov_b64_e32 v[104:105], 0
	v_mov_b64_e32 v[106:107], 0
	v_mov_b64_e32 v[108:109], 0
	v_mov_b64_e32 v[110:111], 0
	v_mov_b64_e32 v[116:117], 0
	v_mov_b64_e32 v[118:119], 0
	v_mov_b64_e32 v[124:125], 0
	v_mov_b64_e32 v[126:127], 0

; template <class Epi, class Sched, bool ALIGN_EPI = false, bool SP2 = false, bool F16 = false, bool TOKPERM = false>
; __device__ __forceinline__ void gemm_phase(PG8_LAS unsigned char* lds, const Gemm g, const Sched& S, const Epi& E, int wv) {
;     ...
;         const bool has_next = S.next(ui + 1, nxt);
;         const char* nA = has_next ? (const char*)g.A + (size_t)nxt.pm * tstep : cA; const char* nB = has_next ? (const char*)g.Bt + (size_t)nxt.pn * tstep : cB;
;     ...
; #pragma unroll
;         for (int a = 0; a < 2; ++a)
; #pragma unroll
;             for (int b = 0; b < 2; ++b)
; #pragma unroll
;                 for (int m = 0; m < 4; ++m)
; #pragma unroll
;                     for (int n = 0; n < 2; ++n) acc[a][b][m][n] = (f32x4){0.f, 0.f, 0.f, 0.f};
.LBB0_1117:
	s_ashr_i32 s79, s78, 31
	s_lshl_b64 s[14:15], s[78:79], 19
	s_add_u32 s80, s40, s14
	s_addc_u32 s81, s41, s15
	s_and_b64 s[14:15], s[6:7], exec
	s_cselect_b32 s9, s81, s11
	s_cselect_b32 s18, s80, s10
	s_ashr_i32 s77, s76, 31
	s_lshl_b64 s[14:15], s[76:77], 19
	s_add_u32 s82, s0, s14
	s_addc_u32 s83, s1, s15
	s_and_b64 s[14:15], s[6:7], exec
	s_cselect_b32 s19, s83, s13
	s_cselect_b32 s58, s82, s12
	s_add_u32 s59, s12, 0x100
	v_mov_b64_e32 v[0:1], 0
	s_addc_u32 s62, s13, 0
	s_mov_b32 s63, -2
	s_waitcnt lgkmcnt(0)
	v_mov_b64_e32 v[2:3], 0
	v_mov_b64_e32 v[16:17], 0
	v_mov_b64_e32 v[18:19], 0
	v_mov_b64_e32 v[4:5], 0
	v_mov_b64_e32 v[6:7], 0
	v_mov_b64_e32 v[20:21], 0
	v_mov_b64_e32 v[22:23], 0
	v_mov_b64_e32 v[8:9], 0
	v_mov_b64_e32 v[10:11], 0
	v_mov_b64_e32 v[24:25], 0
	v_mov_b64_e32 v[26:27], 0
	v_mov_b64_e32 v[12:13], 0
	v_mov_b64_e32 v[14:15], 0
	v_mov_b64_e32 v[28:29], 0
	v_mov_b64_e32 v[30:31], 0
	v_mov_b64_e32 v[32:33], 0
	v_mov_b64_e32 v[34:35], 0
	v_mov_b64_e32 v[48:49], 0
	v_mov_b64_e32 v[50:51], 0
	v_mov_b64_e32 v[36:37], 0
	v_mov_b64_e32 v[38:39], 0
	v_mov_b64_e32 v[52:53], 0
	v_mov_b64_e32 v[54:55], 0
	v_mov_b64_e32 v[40:41], 0
	v_mov_b64_e32 v[42:43], 0
	v_mov_b64_e32 v[56:57], 0
	v_mov_b64_e32 v[58:59], 0
	v_mov_b64_e32 v[44:45], 0
	v_mov_b64_e32 v[46:47], 0
	v_mov_b64_e32 v[60:61], 0
	v_mov_b64_e32 v[62:63], 0
	v_mov_b64_e32 v[64:65], 0
	v_mov_b64_e32 v[66:67], 0
	v_mov_b64_e32 v[80:81], 0
	v_mov_b64_e32 v[82:83], 0
	v_mov_b64_e32 v[68:69], 0
	v_mov_b64_e32 v[70:71], 0
	v_mov_b64_e32 v[84:85], 0
	v_mov_b64_e32 v[86:87], 0
	v_mov_b64_e32 v[72:73], 0
	v_mov_b64_e32 v[74:75], 0
	v_mov_b64_e32 v[88:89], 0
	v_mov_b64_e32 v[90:91], 0
	v_mov_b64_e32 v[76:77], 0
	v_mov_b64_e32 v[78:79], 0
	v_mov_b64_e32 v[92:93], 0
	v_mov_b64_e32 v[94:95], 0
	v_mov_b64_e32 v[96:97], 0
	v_mov_b64_e32 v[98:99], 0
	v_mov_b64_e32 v[112:113], 0
	v_mov_b64_e32 v[114:115], 0
	v_mov_b64_e32 v[100:101], 0
	v_mov_b64_e32 v[102:103], 0
	v_mov_b64_e32 v[116:117], 0
	v_mov_b64_e32 v[118:119], 0
	v_mov_b64_e32 v[104:105], 0
	v_mov_b64_e32 v[106:107], 0
	v_mov_b64_e32 v[120:121], 0
	v_mov_b64_e32 v[122:123], 0
	v_mov_b64_e32 v[108:109], 0
	v_mov_b64_e32 v[110:111], 0
	v_mov_b64_e32 v[124:125], 0
	v_mov_b64_e32 v[126:127], 0

; template <class Epi, class Sched, bool ALIGN_EPI = false, bool SP2 = false, bool F16 = false, bool TOKPERM = false>
; __device__ __forceinline__ void gemm_phase(PG8_LAS unsigned char* lds, const Gemm g, const Sched& S, const Epi& E, int wv) {
;     ...
;         const bool has_next = S.next(ui + 1, nxt);
;         const char* nA = has_next ? (const char*)g.A + (size_t)nxt.pm * tstep : cA; const char* nB = has_next ? (const char*)g.Bt + (size_t)nxt.pn * tstep : cB;
;     ...
; #pragma unroll
;         for (int a = 0; a < 2; ++a)
; #pragma unroll
;             for (int b = 0; b < 2; ++b)
; #pragma unroll
;                 for (int m = 0; m < 4; ++m)
; #pragma unroll
;                     for (int n = 0; n < 2; ++n) acc[a][b][m][n] = (f32x4){0.f, 0.f, 0.f, 0.f};
.LBB0_1523:
	s_ashr_i32 s15, s14, 31
	v_cmp_lt_i64_e32 vcc, s[16:17], v[142:143]
	s_lshl_b64 s[16:17], s[14:15], 19
	s_add_u32 s16, s30, s16
	s_addc_u32 s17, s31, s17
	s_and_b64 s[18:19], vcc, exec
	s_cselect_b32 s15, s17, s25
	s_cselect_b32 s21, s16, s24
	s_ashr_i32 s13, s12, 31
	s_lshl_b64 s[18:19], s[12:13], 19
	s_add_u32 s18, s1, s18
	s_addc_u32 s19, s2, s19
	s_and_b64 s[46:47], vcc, exec
	s_cselect_b32 s13, s19, s45
	s_cselect_b32 s62, s18, s44
	s_add_u32 s24, s24, 0x40080
	s_addc_u32 s25, s25, 0
	s_add_u32 s63, s44, 0x100
	v_mov_b64_e32 v[0:1], 0
	s_addc_u32 s64, s45, 0
	s_mov_b32 s65, -2
	s_waitcnt lgkmcnt(0)
	v_mov_b64_e32 v[2:3], 0
	v_mov_b64_e32 v[4:5], 0
	v_mov_b64_e32 v[6:7], 0
	v_mov_b64_e32 v[16:17], 0
	v_mov_b64_e32 v[18:19], 0
	v_mov_b64_e32 v[20:21], 0
	v_mov_b64_e32 v[22:23], 0
	v_mov_b64_e32 v[32:33], 0
	v_mov_b64_e32 v[34:35], 0
	v_mov_b64_e32 v[36:37], 0
	v_mov_b64_e32 v[38:39], 0
	v_mov_b64_e32 v[48:49], 0
	v_mov_b64_e32 v[50:51], 0
	v_mov_b64_e32 v[52:53], 0
	v_mov_b64_e32 v[54:55], 0
	v_mov_b64_e32 v[8:9], 0
	v_mov_b64_e32 v[10:11], 0
	v_mov_b64_e32 v[12:13], 0
	v_mov_b64_e32 v[14:15], 0
	v_mov_b64_e32 v[24:25], 0
	v_mov_b64_e32 v[26:27], 0
	v_mov_b64_e32 v[28:29], 0
	v_mov_b64_e32 v[30:31], 0
	v_mov_b64_e32 v[40:41], 0
	v_mov_b64_e32 v[42:43], 0
	v_mov_b64_e32 v[44:45], 0
	v_mov_b64_e32 v[46:47], 0
	v_mov_b64_e32 v[56:57], 0
	v_mov_b64_e32 v[58:59], 0
	v_mov_b64_e32 v[60:61], 0
	v_mov_b64_e32 v[62:63], 0
	v_mov_b64_e32 v[64:65], 0
	v_mov_b64_e32 v[66:67], 0
	v_mov_b64_e32 v[68:69], 0
	v_mov_b64_e32 v[70:71], 0
	v_mov_b64_e32 v[80:81], 0
	v_mov_b64_e32 v[82:83], 0
	v_mov_b64_e32 v[84:85], 0
	v_mov_b64_e32 v[86:87], 0
	v_mov_b64_e32 v[96:97], 0
	v_mov_b64_e32 v[98:99], 0
	v_mov_b64_e32 v[100:101], 0
	v_mov_b64_e32 v[102:103], 0
	v_mov_b64_e32 v[112:113], 0
	v_mov_b64_e32 v[114:115], 0
	v_mov_b64_e32 v[116:117], 0
	v_mov_b64_e32 v[118:119], 0
	v_mov_b64_e32 v[72:73], 0
	v_mov_b64_e32 v[74:75], 0
	v_mov_b64_e32 v[76:77], 0
	v_mov_b64_e32 v[78:79], 0
	v_mov_b64_e32 v[88:89], 0
	v_mov_b64_e32 v[90:91], 0
	v_mov_b64_e32 v[92:93], 0
	v_mov_b64_e32 v[94:95], 0
	v_mov_b64_e32 v[104:105], 0
	v_mov_b64_e32 v[106:107], 0
	v_mov_b64_e32 v[108:109], 0
	v_mov_b64_e32 v[110:111], 0
	v_mov_b64_e32 v[120:121], 0
	v_mov_b64_e32 v[122:123], 0
	v_mov_b64_e32 v[124:125], 0
	v_mov_b64_e32 v[126:127], 0

; template <class Epi, class Sched, bool ALIGN_EPI = false, bool SP2 = false, bool F16 = false, bool TOKPERM = false>
; __device__ __forceinline__ void gemm_phase(PG8_LAS unsigned char* lds, const Gemm g, const Sched& S, const Epi& E, int wv) {
;     ...
;         const bool has_next = S.next(ui + 1, nxt);
;         const char* nA = has_next ? (const char*)g.A + (size_t)nxt.pm * tstep : cA; const char* nB = has_next ? (const char*)g.Bt + (size_t)nxt.pn * tstep : cB;
;     ...
; #pragma unroll
;         for (int a = 0; a < 2; ++a)
; #pragma unroll
;             for (int b = 0; b < 2; ++b)
; #pragma unroll
;                 for (int m = 0; m < 4; ++m)
; #pragma unroll
;                     for (int n = 0; n < 2; ++n) acc[a][b][m][n] = (f32x4){0.f, 0.f, 0.f, 0.f};
.LBB0_1606:
	s_ashr_i32 s25, s24, 31
	s_lshl_b64 s[36:37], s[24:25], 19
	s_add_u32 s36, s40, s36
	s_addc_u32 s37, s41, s37
	s_and_b64 s[42:43], s[4:5], exec
	s_cselect_b32 s25, s37, s9
	s_cselect_b32 s64, s36, s8
	s_ashr_i32 s23, s22, 31
	s_lshl_b64 s[42:43], s[22:23], 19
	s_add_u32 s42, s0, s42
	s_addc_u32 s43, s1, s43
	s_and_b64 s[44:45], s[4:5], exec
	s_cselect_b32 s23, s43, s11
	s_cselect_b32 s65, s42, s10
	s_add_u32 s8, s8, 0x40080
	s_addc_u32 s9, s9, 0
	s_add_u32 s66, s10, 0x100
	v_mov_b64_e32 v[0:1], 0
	s_addc_u32 s67, s11, 0
	s_mov_b32 s68, -2
	v_mov_b64_e32 v[2:3], 0
	v_mov_b64_e32 v[4:5], 0
	v_mov_b64_e32 v[6:7], 0
	v_mov_b64_e32 v[16:17], 0
	v_mov_b64_e32 v[18:19], 0
	v_mov_b64_e32 v[20:21], 0
	v_mov_b64_e32 v[22:23], 0
	v_mov_b64_e32 v[32:33], 0
	v_mov_b64_e32 v[34:35], 0
	v_mov_b64_e32 v[36:37], 0
	v_mov_b64_e32 v[38:39], 0
	v_mov_b64_e32 v[48:49], 0
	v_mov_b64_e32 v[50:51], 0
	v_mov_b64_e32 v[52:53], 0
	v_mov_b64_e32 v[54:55], 0
	v_mov_b64_e32 v[8:9], 0
	v_mov_b64_e32 v[10:11], 0
	v_mov_b64_e32 v[12:13], 0
	v_mov_b64_e32 v[14:15], 0
	v_mov_b64_e32 v[24:25], 0
	v_mov_b64_e32 v[26:27], 0
	v_mov_b64_e32 v[28:29], 0
	v_mov_b64_e32 v[30:31], 0
	v_mov_b64_e32 v[40:41], 0
	v_mov_b64_e32 v[42:43], 0
	v_mov_b64_e32 v[44:45], 0
	v_mov_b64_e32 v[46:47], 0
	v_mov_b64_e32 v[56:57], 0
	v_mov_b64_e32 v[58:59], 0
	v_mov_b64_e32 v[60:61], 0
	v_mov_b64_e32 v[62:63], 0
	v_mov_b64_e32 v[64:65], 0
	v_mov_b64_e32 v[66:67], 0
	v_mov_b64_e32 v[68:69], 0
	v_mov_b64_e32 v[70:71], 0
	v_mov_b64_e32 v[80:81], 0
	v_mov_b64_e32 v[82:83], 0
	v_mov_b64_e32 v[84:85], 0
	v_mov_b64_e32 v[86:87], 0
	v_mov_b64_e32 v[96:97], 0
	v_mov_b64_e32 v[98:99], 0
	v_mov_b64_e32 v[100:101], 0
	v_mov_b64_e32 v[102:103], 0
	v_mov_b64_e32 v[112:113], 0
	v_mov_b64_e32 v[114:115], 0
	v_mov_b64_e32 v[120:121], 0
	v_mov_b64_e32 v[122:123], 0
	v_mov_b64_e32 v[72:73], 0
	v_mov_b64_e32 v[74:75], 0
	v_mov_b64_e32 v[76:77], 0
	v_mov_b64_e32 v[78:79], 0
	v_mov_b64_e32 v[88:89], 0
	v_mov_b64_e32 v[90:91], 0
	v_mov_b64_e32 v[92:93], 0
	v_mov_b64_e32 v[94:95], 0
	v_mov_b64_e32 v[104:105], 0
	v_mov_b64_e32 v[106:107], 0
	v_mov_b64_e32 v[108:109], 0
	v_mov_b64_e32 v[110:111], 0
	v_mov_b64_e32 v[116:117], 0
	v_mov_b64_e32 v[118:119], 0
	v_mov_b64_e32 v[124:125], 0
	v_mov_b64_e32 v[126:127], 0

; template <class Epi, class Sched, bool ALIGN_EPI = false, bool SP2 = false, bool F16 = false, bool TOKPERM = false>
; __device__ __forceinline__ void gemm_phase(PG8_LAS unsigned char* lds, const Gemm g, const Sched& S, const Epi& E, int wv) {
;     ...
; #pragma unroll
;         for (int a = 0; a < 2; ++a)
; #pragma unroll
;             for (int b = 0; b < 2; ++b)
; #pragma unroll
;                 for (int m = 0; m < 4; ++m)
; #pragma unroll
;                     for (int n = 0; n < 2; ++n) acc[a][b][m][n] = (f32x4){0.f, 0.f, 0.f, 0.f};
.LBB0_1686:
	s_add_u32 s51, s10, 0x100
	v_mov_b64_e32 v[0:1], 0
	s_addc_u32 s52, s11, 0
	s_mov_b32 s53, -2
	v_mov_b64_e32 v[2:3], 0
	v_mov_b64_e32 v[4:5], 0
	v_mov_b64_e32 v[6:7], 0
	v_mov_b64_e32 v[16:17], 0
	v_mov_b64_e32 v[18:19], 0
	v_mov_b64_e32 v[20:21], 0
	v_mov_b64_e32 v[22:23], 0
	v_mov_b64_e32 v[32:33], 0
	v_mov_b64_e32 v[34:35], 0
	v_mov_b64_e32 v[36:37], 0
	v_mov_b64_e32 v[38:39], 0
	v_mov_b64_e32 v[48:49], 0
	v_mov_b64_e32 v[50:51], 0
	v_mov_b64_e32 v[52:53], 0
	v_mov_b64_e32 v[54:55], 0
	v_mov_b64_e32 v[8:9], 0
	v_mov_b64_e32 v[10:11], 0
	v_mov_b64_e32 v[12:13], 0
	v_mov_b64_e32 v[14:15], 0
	v_mov_b64_e32 v[24:25], 0
	v_mov_b64_e32 v[26:27], 0
	v_mov_b64_e32 v[28:29], 0
	v_mov_b64_e32 v[30:31], 0
	v_mov_b64_e32 v[40:41], 0
	v_mov_b64_e32 v[42:43], 0
	v_mov_b64_e32 v[44:45], 0
	v_mov_b64_e32 v[46:47], 0
	v_mov_b64_e32 v[56:57], 0
	v_mov_b64_e32 v[58:59], 0
	v_mov_b64_e32 v[60:61], 0
	v_mov_b64_e32 v[62:63], 0
	v_mov_b64_e32 v[64:65], 0
	v_mov_b64_e32 v[66:67], 0
	v_mov_b64_e32 v[68:69], 0
	v_mov_b64_e32 v[70:71], 0
	v_mov_b64_e32 v[80:81], 0
	v_mov_b64_e32 v[82:83], 0
	v_mov_b64_e32 v[84:85], 0
	v_mov_b64_e32 v[86:87], 0
	v_mov_b64_e32 v[96:97], 0
	v_mov_b64_e32 v[98:99], 0
	v_mov_b64_e32 v[100:101], 0
	v_mov_b64_e32 v[102:103], 0
	v_mov_b64_e32 v[112:113], 0
	v_mov_b64_e32 v[114:115], 0
	v_mov_b64_e32 v[116:117], 0
	v_mov_b64_e32 v[118:119], 0
	v_mov_b64_e32 v[72:73], 0
	v_mov_b64_e32 v[74:75], 0
	v_mov_b64_e32 v[76:77], 0
	v_mov_b64_e32 v[78:79], 0
	v_mov_b64_e32 v[88:89], 0
	v_mov_b64_e32 v[90:91], 0
	v_mov_b64_e32 v[92:93], 0
	v_mov_b64_e32 v[94:95], 0
	v_mov_b64_e32 v[104:105], 0
	v_mov_b64_e32 v[106:107], 0
	v_mov_b64_e32 v[108:109], 0
	v_mov_b64_e32 v[110:111], 0
	v_mov_b64_e32 v[120:121], 0
	v_mov_b64_e32 v[122:123], 0
	v_mov_b64_e32 v[124:125], 0
	v_mov_b64_e32 v[126:127], 0
